# MIX1: mixed first items (even workgroups HGRN pass 1, odd ones LRU pass A), remaining HGRN pass-1 items next, then cycles of 5 LRU + 4 sample HGRN + 24 attention
# speedup vs baseline: 1.0039x; 1.0039x over previous
.LBB0_510:
	s_andn2_b64 vcc, exec, s[2:3]
	s_cbranch_vccnz .LBB0_1032
	v_readlane_b32 s2, v254, 55
	s_cmp_gt_i32 s2, 0
	s_mov_b64 s[2:3], -1
	s_cbranch_scc0 .LBB0_791
	v_readlane_b32 s2, v251, 56
	v_readlane_b32 s3, v251, 57
	s_andn2_b64 vcc, exec, s[2:3]
	s_cbranch_vccnz .LBB0_790
	v_readlane_b32 s12, v254, 51
	v_readlane_b32 s13, v254, 52
	s_and_b64 s[2:3], s[12:13], exec
	s_movk_i32 s2, 0x200
	s_cselect_b32 s2, s2, 0x100
	s_add_u32 s2, s8, s2
	s_addc_u32 s3, s9, 0
	v_writelane_b32 v254, s2, 58
	v_readlane_b32 s44, v252, 4
	v_readlane_b32 s58, v252, 18
	v_writelane_b32 v254, s3, 59
	s_add_u32 s2, s8, 0x36900000
	s_addc_u32 s3, s9, 0
	v_writelane_b32 v254, s2, 60
	v_readlane_b32 s59, v252, 19
	v_readlane_b32 s24, v253, 58
	v_writelane_b32 v254, s3, 61
	s_add_u32 s2, s8, 0x38200000
	s_addc_u32 s3, s9, 0
	v_writelane_b32 v254, s2, 62
	s_add_u32 s83, s8, 0x17000400
	v_readlane_b32 s28, v253, 62
	v_writelane_b32 v254, s3, 63
	s_addc_u32 s2, s9, 0
	v_writelane_b32 v255, s2, 0
	s_add_u32 s2, s8, 0x38400000
	v_writelane_b32 v255, s2, 1
	s_addc_u32 s2, s9, 0
	v_writelane_b32 v255, s2, 2
	s_add_u32 s2, s8, 0x3a400000
	v_writelane_b32 v255, s2, 3
	s_addc_u32 s2, s9, 0
	v_writelane_b32 v255, s2, 4
	s_and_b64 s[2:3], s[12:13], exec
	s_cselect_b32 s2, 0x2000, 0
	s_add_u32 s2, s58, s2
	s_addc_u32 s3, s59, 0
	v_writelane_b32 v255, s2, 5
	v_readlane_b32 s29, v253, 63
	v_readlane_b32 s45, v252, 5
	v_writelane_b32 v255, s3, 6
	s_and_b64 s[2:3], s[12:13], exec
	s_cselect_b32 s2, 32, 0
	v_writelane_b32 v255, s2, 7
	s_cselect_b32 s2, 0x20000, 0
	s_cselect_b32 s95, 0x200, 0
	s_add_u32 s2, s8, s2
	s_addc_u32 s3, s9, 0
	s_add_u32 s22, s2, 0x36800000
	s_addc_u32 s23, s3, 0
	s_and_b64 s[2:3], s[12:13], exec
	s_cselect_b32 s2, 0x10000, 0
	s_add_u32 s3, s42, s2
	v_writelane_b32 v255, s3, 9
	s_addc_u32 s3, s43, 0
	v_writelane_b32 v255, s3, 11
	s_add_u32 s2, s28, s2
	v_writelane_b32 v255, s2, 13
	s_addc_u32 s2, s29, 0
	v_writelane_b32 v255, s2, 14
	s_and_b64 s[2:3], s[12:13], exec
	s_cselect_b32 s2, 0x1800, 0
	v_readlane_b32 s3, v251, 62
	s_add_u32 s12, s3, s2
	v_readlane_b32 s2, v251, 63
	s_addc_u32 s13, s2, 0
	s_add_u32 s34, s8, 0x3df00000
	v_writelane_b32 v255, s12, 15
	s_addc_u32 s35, s9, 0
	s_add_u32 s2, s8, 0x36600000
	v_writelane_b32 v255, s13, 16
	v_writelane_b32 v255, s2, 17
	s_addc_u32 s2, s9, 0
	v_writelane_b32 v255, s2, 18
	v_readlane_b32 s2, v254, 3
	v_readlane_b32 s46, v252, 6
	v_readlane_b32 s47, v252, 7
	v_readlane_b32 s48, v252, 8
	v_readlane_b32 s49, v252, 9
	v_readlane_b32 s50, v252, 10
	v_readlane_b32 s51, v252, 11
	v_readlane_b32 s52, v252, 12
	v_readlane_b32 s53, v252, 13
	v_readlane_b32 s54, v252, 14
	v_readlane_b32 s55, v252, 15
	v_readlane_b32 s56, v252, 16
	v_readlane_b32 s57, v252, 17
	v_readlane_b32 s25, v253, 59
	v_readlane_b32 s26, v253, 60
	v_readlane_b32 s27, v253, 61
	v_readlane_b32 s30, v254, 0
	v_readlane_b32 s31, v254, 1
	v_readlane_b32 s3, v254, 4
	v_readlane_b32 s14, v251, 8
	s_cmp_lg_u32 s14, 0
	s_cbranch_scc0 .Lq_first_done
	s_and_b32 s14, s2, 1
	s_lshr_b32 s2, s2, 1
	s_cmp_eq_u32 s14, 0
	s_cselect_b32 s14, 0x120, 0
	s_add_i32 s2, s2, s14
.Lq_first_done:
	s_branch .LBB0_516
.LBB0_514:
	s_or_b64 exec, exec, s[24:25]
	s_waitcnt vmcnt(0)
	v_readfirstlane_b32 s14, v2
	v_readlane_b32 s12, v251, 8
	s_cmp_lg_u32 s12, 0
	s_cbranch_scc1 .Lq_map
	s_add_i32 s14, s92, s14
	s_branch .Lq_mapped
.Lq_map:
	s_cmpk_ge_u32 s14, 0x4a0
	s_cbranch_scc1 .Lq_end
	s_cmpk_ge_u32 s14, 0x80
	s_cbranch_scc1 .Lq_cyc
	s_addk_i32 s14, 0x1a0
	s_branch .Lq_mapped
.Lq_cyc:
	s_addk_i32 s14, 0xff80
	s_mul_hi_u32 s12, s14, 0x7c1f07d
	s_mul_i32 s13, s12, 33
	s_sub_i32 s13, s14, s13
	s_cmpk_ge_u32 s13, 5
	s_cbranch_scc1 .Lq_k2
	s_mul_i32 s14, s12, 5
	s_add_i32 s14, s14, s13
	s_addk_i32 s14, 0x80
	s_branch .Lq_mapped
.Lq_k2:
	s_cmpk_ge_u32 s13, 9
	s_cbranch_scc1 .Lq_k3
	s_lshl_b32 s14, s12, 2
	s_add_i32 s14, s14, s13
	s_addk_i32 s14, 0x21b
	s_branch .Lq_mapped
